# RG-LRU a/bx stores use default cache policy (loads keep nt)
# baseline (speedup 1.0000x reference)
.LBB0_629:
	s_or_b64 exec, exec, s[6:7]
	v_ashrrev_i32_e32 v3, 2, v2
	v_and_b32_e32 v14, 15, v2
	v_bfi_b32 v18, -16, v3, v2
	v_mul_lo_u32 v6, v18, s88
	v_and_b32_e32 v0, 48, v2
	v_readlane_b32 s6, v254, 24
	v_mul_u32_u24_e32 v14, 0x90, v14
	v_readlane_b32 s20, v254, 20
	v_add3_u32 v6, s6, v6, v0
	v_lshlrev_b32_e32 v15, 8, v18
	v_readlane_b32 s6, v254, 26
	v_add_u32_e32 v24, 0, v0
	v_add3_u32 v47, s20, v0, v14
	s_waitcnt lgkmcnt(0)
	s_barrier
	ds_read_b128 v[10:13], v6
	ds_read_b128 v[6:9], v6 offset:64
	v_add3_u32 v45, s6, v15, v0
	v_add_u32_e32 v44, v24, v15
	ds_read_b128 v[14:17], v47 offset:9216
	s_or_b32 s17, s29, s30
	v_add_u32_e32 v42, s17, v18
	ds_read_b128 v[18:21], v47 offset:9280
	s_waitcnt lgkmcnt(0)
	v_mfma_f32_16x16x32_bf16 v[14:17], v[14:17], v[10:13], 0
	v_add_u32_e32 v46, 0x22500, v24
	ds_read_b128 v[32:35], v47
	ds_read_b128 v[24:27], v46 offset:512
	v_mfma_f32_16x16x32_bf16 v[28:31], v[18:21], v[6:9], v[14:17]
	s_add_u32 s6, s0, s4
	s_addc_u32 s7, s1, s5
	ds_read_b128 v[36:39], v47 offset:64
	s_add_u32 s4, s6, 0x16400000
	s_addc_u32 s5, s7, 0
	s_waitcnt lgkmcnt(0)
	s_nop 1
	v_add_f32_e32 v14, v28, v24
	v_mul_f32_e32 v14, 0xbfb8aa3b, v14
	v_exp_f32_e32 v20, v14
	v_mov_b64_e32 v[22:23], s[4:5]
	s_movk_i32 s17, 0xc00
	v_mad_i64_i32 v[22:23], s[4:5], v42, s17, v[22:23]
	v_add_f32_e32 v20, 1.0, v20
	v_lshl_add_u64 v[40:41], v[22:23], 0, v[0:1]
	v_mfma_f32_16x16x32_bf16 v[14:17], v[32:35], v[10:13], 0
	v_rcp_f32_e32 v24, v20
	ds_read_b128 v[20:23], v46
	s_add_u32 s6, s6, 0x19400000
	s_addc_u32 s7, s7, 0
	v_mov_b64_e32 v[18:19], s[6:7]
	v_mad_i64_i32 v[42:43], s[4:5], v42, s17, v[18:19]
	ds_read_b128 v[32:35], v46 offset:256
	v_mfma_f32_16x16x32_bf16 v[16:19], v[36:39], v[6:9], v[14:17]
	ds_read_b128 v[36:39], v44 offset:33792
	v_lshl_add_u64 v[42:43], v[42:43], 0, v[0:1]
	v_add_f32_e32 v25, v29, v25
	v_mul_f32_e32 v14, 0x41000000, v24
	s_waitcnt lgkmcnt(0)
	v_mul_f32_e32 v14, v20, v14
	v_mul_f32_e32 v14, 0x3fb8aa3b, v14
	v_exp_f32_e32 v14, v14
	v_add_f32_e32 v15, v16, v32
	v_mul_f32_e32 v15, 0xbfb8aa3b, v15
	v_exp_f32_e32 v15, v15
	v_fma_f32 v16, -v14, v14, 1.0
	v_max_f32_e32 v16, 0, v16
	v_cmp_gt_f32_e32 vcc, s85, v16
	v_mul_f32_e32 v20, 0x4f800000, v16
	v_add_f32_e32 v0, 1.0, v15
	v_cndmask_b32_e32 v16, v16, v20, vcc
	v_sqrt_f32_e32 v24, v16
	v_rcp_f32_e32 v20, v0
	v_mul_f32_e32 v25, 0xbfb8aa3b, v25
	v_exp_f32_e32 v25, v25
	v_add_u32_e32 v0, -1, v24
	v_fma_f32 v15, -v0, v24, v16
	v_cmp_ge_f32_e64 s[4:5], 0, v15
	v_add_u32_e32 v15, 1, v24
	v_add_f32_e32 v17, v17, v33
	v_cndmask_b32_e64 v0, v24, v0, s[4:5]
	v_fma_f32 v24, -v15, v24, v16
	v_cmp_lt_f32_e64 s[4:5], 0, v24
	v_mul_f32_e32 v17, 0xbfb8aa3b, v17
	v_exp_f32_e32 v17, v17
	v_cndmask_b32_e64 v0, v0, v15, s[4:5]
	v_add_f32_e32 v15, 1.0, v25
	v_rcp_f32_e32 v15, v15
	v_mul_f32_e32 v24, 0x37800000, v0
	v_cndmask_b32_e32 v0, v0, v24, vcc
	v_cmp_class_f32_e32 vcc, v16, v221
	v_mul_f32_e32 v15, 0x41000000, v15
	v_mul_f32_e32 v15, v21, v15
	v_mul_f32_e32 v15, 0x3fb8aa3b, v15
	v_exp_f32_e32 v15, v15
	v_add_f32_e32 v26, v30, v26
	v_mul_f32_e32 v26, 0xbfb8aa3b, v26
	v_exp_f32_e32 v26, v26
	v_fma_f32 v21, -v15, v15, 1.0
	v_max_f32_e32 v21, 0, v21
	v_cmp_gt_f32_e64 s[4:5], s85, v21
	v_mul_f32_e32 v24, 0x4f800000, v21
	v_add_f32_e32 v27, v31, v27
	v_cndmask_b32_e64 v25, v21, v24, s[4:5]
	v_sqrt_f32_e32 v28, v25
	v_cndmask_b32_e32 v24, v0, v16, vcc
	v_add_f32_e32 v0, 1.0, v17
	v_rcp_f32_e32 v21, v0
	v_add_u32_e32 v0, -1, v28
	v_fma_f32 v16, -v0, v28, v25
	v_cmp_ge_f32_e32 vcc, 0, v16
	v_add_u32_e32 v16, 1, v28
	v_fma_f32 v17, -v16, v28, v25
	v_cndmask_b32_e32 v0, v28, v0, vcc
	v_cmp_lt_f32_e32 vcc, 0, v17
	v_add_f32_e32 v17, 1.0, v26
	v_rcp_f32_e32 v17, v17
	v_cndmask_b32_e32 v0, v0, v16, vcc
	v_mul_f32_e32 v16, 0x37800000, v0
	v_cndmask_b32_e64 v0, v0, v16, s[4:5]
	v_cmp_class_f32_e32 vcc, v25, v221
	v_mul_f32_e32 v27, 0xbfb8aa3b, v27
	v_exp_f32_e32 v27, v27
	v_cndmask_b32_e32 v25, v0, v25, vcc
	v_mul_f32_e32 v0, 0x41000000, v17
	v_mul_f32_e32 v0, v22, v0
	v_mul_f32_e32 v0, 0x3fb8aa3b, v0
	v_exp_f32_e32 v16, v0
	v_add_f32_e32 v0, v18, v34
	v_mul_f32_e32 v0, 0xbfb8aa3b, v0
	v_exp_f32_e32 v18, v0
	v_fma_f32 v0, -v16, v16, 1.0
	v_max_f32_e32 v0, 0, v0
	v_cmp_gt_f32_e32 vcc, s85, v0
	v_mul_f32_e32 v17, 0x4f800000, v0
	v_add_f32_e32 v19, v19, v35
	v_cndmask_b32_e32 v0, v0, v17, vcc
	v_sqrt_f32_e32 v17, v0
	v_mul_f32_e32 v19, 0xbfb8aa3b, v19
	v_exp_f32_e32 v19, v19
	v_add_f32_e32 v18, 1.0, v18
	v_add_u32_e32 v22, -1, v17
	v_fma_f32 v26, -v22, v17, v0
	v_cmp_ge_f32_e64 s[4:5], 0, v26
	v_add_u32_e32 v26, 1, v17
	v_rcp_f32_e32 v18, v18
	v_cndmask_b32_e64 v22, v17, v22, s[4:5]
	v_fma_f32 v17, -v26, v17, v0
	v_cmp_lt_f32_e64 s[4:5], 0, v17
	v_pk_mul_f32 v[20:21], v[20:21], v[24:25]
	s_nop 0
	v_cndmask_b32_e64 v17, v22, v26, s[4:5]
	v_add_f32_e32 v22, 1.0, v27
	v_rcp_f32_e32 v22, v22
	v_mul_f32_e32 v26, 0x37800000, v17
	v_cndmask_b32_e32 v26, v17, v26, vcc
	v_cmp_class_f32_e32 vcc, v0, v221
	v_mul_f32_e32 v17, 0x41000000, v22
	v_mul_f32_e32 v17, v23, v17
	v_mul_f32_e32 v17, 0x3fb8aa3b, v17
	v_exp_f32_e32 v17, v17
	s_nop 0
	v_fma_f32 v22, -v17, v17, 1.0
	v_max_f32_e32 v22, 0, v22
	v_cmp_gt_f32_e64 s[4:5], s85, v22
	v_mul_f32_e32 v23, 0x4f800000, v22
	s_nop 0
	v_cndmask_b32_e64 v23, v22, v23, s[4:5]
	v_sqrt_f32_e32 v27, v23
	v_cndmask_b32_e32 v22, v26, v0, vcc
	v_add_f32_e32 v0, 1.0, v19
	v_rcp_f32_e32 v19, v0
	v_add_u32_e32 v0, -1, v27
	v_fma_f32 v26, -v0, v27, v23
	v_cmp_ge_f32_e32 vcc, 0, v26
	v_add_u32_e32 v26, 1, v27
	s_nop 0
	v_cndmask_b32_e32 v0, v27, v0, vcc
	v_fma_f32 v27, -v26, v27, v23
	v_cmp_lt_f32_e32 vcc, 0, v27
	s_nop 1
	v_cndmask_b32_e32 v0, v0, v26, vcc
	v_mul_f32_e32 v26, 0x37800000, v0
	v_cndmask_b32_e64 v0, v0, v26, s[4:5]
	v_cmp_class_f32_e32 vcc, v23, v221
	s_nop 1
	v_cndmask_b32_e32 v23, v0, v23, vcc
	v_pk_mul_f32 v[22:23], v[18:19], v[22:23]
	v_pk_mul_f32 v[18:19], v[36:37], v[20:21]
	v_pk_mul_f32 v[20:21], v[38:39], v[22:23]
	ds_write_b128 v45, v[14:17]
	ds_write_b128 v44, v[18:21]
	global_store_dwordx4 v[40:41], v[14:17], off
	global_store_dwordx4 v[42:43], v[18:21], off
	ds_read_b128 v[14:17], v47 offset:11520
	ds_read_b128 v[18:21], v47 offset:11584
	s_waitcnt lgkmcnt(0)
	v_mfma_f32_16x16x32_bf16 v[14:17], v[14:17], v[10:13], 0
	ds_read_b128 v[22:25], v47 offset:2304
	ds_read_b128 v[36:39], v47 offset:2368
	ds_read_b128 v[28:31], v46 offset:576
	v_mfma_f32_16x16x32_bf16 v[32:35], v[18:21], v[6:9], v[14:17]
	s_waitcnt lgkmcnt(0)
	v_mfma_f32_16x16x32_bf16 v[14:17], v[22:25], v[10:13], 0
	ds_read_b128 v[20:23], v46 offset:64
	s_nop 4
	v_add_f32_e32 v0, v32, v28
	v_mul_f32_e32 v0, 0xbfb8aa3b, v0
	v_exp_f32_e32 v0, v0
	v_mfma_f32_16x16x32_bf16 v[16:19], v[36:39], v[6:9], v[14:17]
	ds_read_b128 v[36:39], v44 offset:33856
	ds_read_b128 v[24:27], v46 offset:320
	v_add_f32_e32 v0, 1.0, v0
	v_rcp_f32_e32 v0, v0
	v_add_f32_e32 v28, v33, v29
	v_mul_f32_e32 v28, 0xbfb8aa3b, v28
	v_exp_f32_e32 v28, v28
	v_mul_f32_e32 v0, 0x41000000, v0
	s_waitcnt lgkmcnt(0)
	v_mul_f32_e32 v0, v20, v0
	v_mul_f32_e32 v0, 0x3fb8aa3b, v0
	v_exp_f32_e32 v14, v0
	v_add_f32_e32 v0, v16, v24
	v_mul_f32_e32 v0, 0xbfb8aa3b, v0
	v_exp_f32_e32 v0, v0
	v_fma_f32 v15, -v14, v14, 1.0
	v_max_f32_e32 v15, 0, v15
	v_cmp_gt_f32_e32 vcc, s85, v15
	v_mul_f32_e32 v16, 0x4f800000, v15
	v_add_f32_e32 v0, 1.0, v0
	v_cndmask_b32_e32 v16, v15, v16, vcc
	v_sqrt_f32_e32 v15, v16
	v_rcp_f32_e32 v20, v0
	v_add_f32_e32 v17, v17, v25
	v_mul_f32_e32 v17, 0xbfb8aa3b, v17
	v_add_u32_e32 v0, -1, v15
	v_fma_f32 v24, -v0, v15, v16
	v_cmp_ge_f32_e64 s[4:5], 0, v24
	v_add_u32_e32 v24, 1, v15
	v_exp_f32_e32 v17, v17
	v_cndmask_b32_e64 v0, v15, v0, s[4:5]
	v_fma_f32 v15, -v24, v15, v16
	v_cmp_lt_f32_e64 s[4:5], 0, v15
	v_add_f32_e32 v15, 1.0, v28
	v_rcp_f32_e32 v15, v15
	v_cndmask_b32_e64 v0, v0, v24, s[4:5]
	v_mul_f32_e32 v24, 0x37800000, v0
	v_cndmask_b32_e32 v0, v0, v24, vcc
	v_mul_f32_e32 v15, 0x41000000, v15
	v_mul_f32_e32 v15, v21, v15
	v_mul_f32_e32 v15, 0x3fb8aa3b, v15
	v_exp_f32_e32 v15, v15
	v_cmp_class_f32_e32 vcc, v16, v221
	v_add_f32_e32 v19, v19, v27
	v_mul_f32_e32 v19, 0xbfb8aa3b, v19
	v_fma_f32 v21, -v15, v15, 1.0
	v_max_f32_e32 v21, 0, v21
	v_cmp_gt_f32_e64 s[4:5], s85, v21
	v_mul_f32_e32 v24, 0x4f800000, v21
	v_exp_f32_e32 v19, v19
	v_cndmask_b32_e64 v25, v21, v24, s[4:5]
	v_sqrt_f32_e32 v28, v25
	v_cndmask_b32_e32 v24, v0, v16, vcc
	v_add_f32_e32 v0, 1.0, v17
	v_rcp_f32_e32 v21, v0
	v_add_u32_e32 v0, -1, v28
	v_fma_f32 v16, -v0, v28, v25
	v_cmp_ge_f32_e32 vcc, 0, v16
	v_add_u32_e32 v16, 1, v28
	v_fma_f32 v17, -v16, v28, v25
	v_cndmask_b32_e32 v0, v28, v0, vcc
	v_add_f32_e32 v28, v34, v30
	v_mul_f32_e32 v28, 0xbfb8aa3b, v28
	v_exp_f32_e32 v28, v28
	v_cmp_lt_f32_e32 vcc, 0, v17
	v_add_f32_e32 v17, 1.0, v28
	v_rcp_f32_e32 v17, v17
	v_cndmask_b32_e32 v0, v0, v16, vcc
	v_mul_f32_e32 v16, 0x37800000, v0
	v_cndmask_b32_e64 v0, v0, v16, s[4:5]
	v_cmp_class_f32_e32 vcc, v25, v221
	v_add_f32_e32 v28, v35, v31
	v_mul_f32_e32 v28, 0xbfb8aa3b, v28
	v_cndmask_b32_e32 v25, v0, v25, vcc
	v_mul_f32_e32 v0, 0x41000000, v17
	v_mul_f32_e32 v0, v22, v0
	v_mul_f32_e32 v0, 0x3fb8aa3b, v0
	v_exp_f32_e32 v16, v0
	v_add_f32_e32 v0, v18, v26
	v_mul_f32_e32 v0, 0xbfb8aa3b, v0
	v_exp_f32_e32 v18, v0
	v_fma_f32 v0, -v16, v16, 1.0
	v_max_f32_e32 v0, 0, v0
	v_cmp_gt_f32_e32 vcc, s85, v0
	v_mul_f32_e32 v17, 0x4f800000, v0
	v_exp_f32_e32 v28, v28
	v_cndmask_b32_e32 v0, v0, v17, vcc
	v_sqrt_f32_e32 v17, v0
	v_add_f32_e32 v18, 1.0, v18
	v_rcp_f32_e32 v18, v18
	v_pk_mul_f32 v[20:21], v[20:21], v[24:25]
	v_add_u32_e32 v22, -1, v17
	v_fma_f32 v26, -v22, v17, v0
	v_cmp_ge_f32_e64 s[4:5], 0, v26
	v_add_u32_e32 v26, 1, v17
	s_nop 0
	v_cndmask_b32_e64 v22, v17, v22, s[4:5]
	v_fma_f32 v17, -v26, v17, v0
	v_cmp_lt_f32_e64 s[4:5], 0, v17
	s_nop 1
	v_cndmask_b32_e64 v17, v22, v26, s[4:5]
	v_add_f32_e32 v22, 1.0, v28
	v_rcp_f32_e32 v22, v22
	v_mul_f32_e32 v26, 0x37800000, v17
	v_cndmask_b32_e32 v26, v17, v26, vcc
	v_cmp_class_f32_e32 vcc, v0, v221
	v_mul_f32_e32 v17, 0x41000000, v22
	v_mul_f32_e32 v17, v23, v17
	v_mul_f32_e32 v17, 0x3fb8aa3b, v17
	v_exp_f32_e32 v17, v17
	s_nop 0
	v_fma_f32 v22, -v17, v17, 1.0
	v_max_f32_e32 v22, 0, v22
	v_cmp_gt_f32_e64 s[4:5], s85, v22
	v_mul_f32_e32 v23, 0x4f800000, v22
	s_nop 0
	v_cndmask_b32_e64 v23, v22, v23, s[4:5]
	v_sqrt_f32_e32 v27, v23
	v_cndmask_b32_e32 v22, v26, v0, vcc
	v_add_f32_e32 v0, 1.0, v19
	v_rcp_f32_e32 v19, v0
	v_add_u32_e32 v0, -1, v27
	v_fma_f32 v26, -v0, v27, v23
	v_cmp_ge_f32_e32 vcc, 0, v26
	v_add_u32_e32 v26, 1, v27
	s_nop 0
	v_cndmask_b32_e32 v0, v27, v0, vcc
	v_fma_f32 v27, -v26, v27, v23
	v_cmp_lt_f32_e32 vcc, 0, v27
	s_nop 1
	v_cndmask_b32_e32 v0, v0, v26, vcc
	v_mul_f32_e32 v26, 0x37800000, v0
	v_cndmask_b32_e64 v0, v0, v26, s[4:5]
	v_cmp_class_f32_e32 vcc, v23, v221
	s_nop 1
	v_cndmask_b32_e32 v23, v0, v23, vcc
	v_pk_mul_f32 v[22:23], v[18:19], v[22:23]
	v_pk_mul_f32 v[18:19], v[36:37], v[20:21]
	v_pk_mul_f32 v[20:21], v[38:39], v[22:23]
	ds_write_b128 v45, v[14:17] offset:64
	ds_write_b128 v44, v[18:21] offset:64
	global_store_dwordx4 v[40:41], v[14:17], off offset:64
	global_store_dwordx4 v[42:43], v[18:21], off offset:64
	ds_read_b128 v[14:17], v47 offset:13824
	ds_read_b128 v[18:21], v47 offset:13888
	s_waitcnt lgkmcnt(0)
	v_mfma_f32_16x16x32_bf16 v[14:17], v[14:17], v[10:13], 0
	ds_read_b128 v[22:25], v47 offset:4608
	ds_read_b128 v[36:39], v47 offset:4672
	ds_read_b128 v[28:31], v46 offset:640
	v_mfma_f32_16x16x32_bf16 v[32:35], v[18:21], v[6:9], v[14:17]
	s_waitcnt lgkmcnt(0)
	v_mfma_f32_16x16x32_bf16 v[14:17], v[22:25], v[10:13], 0
	ds_read_b128 v[20:23], v46 offset:128
	s_nop 4
	v_add_f32_e32 v0, v32, v28
	v_mul_f32_e32 v0, 0xbfb8aa3b, v0
	v_exp_f32_e32 v0, v0
	v_mfma_f32_16x16x32_bf16 v[16:19], v[36:39], v[6:9], v[14:17]
	ds_read_b128 v[36:39], v44 offset:33920
	ds_read_b128 v[24:27], v46 offset:384
	v_add_f32_e32 v0, 1.0, v0
	v_rcp_f32_e32 v0, v0
	v_add_f32_e32 v28, v33, v29
	v_mul_f32_e32 v28, 0xbfb8aa3b, v28
	v_exp_f32_e32 v28, v28
	v_mul_f32_e32 v0, 0x41000000, v0
	s_waitcnt lgkmcnt(0)
	v_mul_f32_e32 v0, v20, v0
	v_mul_f32_e32 v0, 0x3fb8aa3b, v0
	v_exp_f32_e32 v14, v0
	v_add_f32_e32 v0, v16, v24
	v_mul_f32_e32 v0, 0xbfb8aa3b, v0
	v_exp_f32_e32 v0, v0
	v_fma_f32 v15, -v14, v14, 1.0
	v_max_f32_e32 v15, 0, v15
	v_cmp_gt_f32_e32 vcc, s85, v15
	v_mul_f32_e32 v16, 0x4f800000, v15
	v_add_f32_e32 v0, 1.0, v0
	v_cndmask_b32_e32 v16, v15, v16, vcc
	v_sqrt_f32_e32 v15, v16
	v_rcp_f32_e32 v20, v0
	v_add_f32_e32 v17, v17, v25
	v_mul_f32_e32 v17, 0xbfb8aa3b, v17
	v_add_u32_e32 v0, -1, v15
	v_fma_f32 v24, -v0, v15, v16
	v_cmp_ge_f32_e64 s[4:5], 0, v24
	v_add_u32_e32 v24, 1, v15
	v_exp_f32_e32 v17, v17
	v_cndmask_b32_e64 v0, v15, v0, s[4:5]
	v_fma_f32 v15, -v24, v15, v16
	v_cmp_lt_f32_e64 s[4:5], 0, v15
	v_add_f32_e32 v15, 1.0, v28
	v_rcp_f32_e32 v15, v15
	v_cndmask_b32_e64 v0, v0, v24, s[4:5]
	v_mul_f32_e32 v24, 0x37800000, v0
	v_cndmask_b32_e32 v0, v0, v24, vcc
	v_mul_f32_e32 v15, 0x41000000, v15
	v_mul_f32_e32 v15, v21, v15
	v_mul_f32_e32 v15, 0x3fb8aa3b, v15
	v_exp_f32_e32 v15, v15
	v_cmp_class_f32_e32 vcc, v16, v221
	v_add_f32_e32 v19, v19, v27
	v_mul_f32_e32 v19, 0xbfb8aa3b, v19
	v_fma_f32 v21, -v15, v15, 1.0
	v_max_f32_e32 v21, 0, v21
	v_cmp_gt_f32_e64 s[4:5], s85, v21
	v_mul_f32_e32 v24, 0x4f800000, v21
	v_exp_f32_e32 v19, v19
	v_cndmask_b32_e64 v25, v21, v24, s[4:5]
	v_sqrt_f32_e32 v28, v25
	v_cndmask_b32_e32 v24, v0, v16, vcc
	v_add_f32_e32 v0, 1.0, v17
	v_rcp_f32_e32 v21, v0
	v_add_u32_e32 v0, -1, v28
	v_fma_f32 v16, -v0, v28, v25
	v_cmp_ge_f32_e32 vcc, 0, v16
	v_add_u32_e32 v16, 1, v28
	v_fma_f32 v17, -v16, v28, v25
	v_cndmask_b32_e32 v0, v28, v0, vcc
	v_add_f32_e32 v28, v34, v30
	v_mul_f32_e32 v28, 0xbfb8aa3b, v28
	v_exp_f32_e32 v28, v28
	v_cmp_lt_f32_e32 vcc, 0, v17
	v_add_f32_e32 v17, 1.0, v28
	v_rcp_f32_e32 v17, v17
	v_cndmask_b32_e32 v0, v0, v16, vcc
	v_mul_f32_e32 v16, 0x37800000, v0
	v_cndmask_b32_e64 v0, v0, v16, s[4:5]
	v_cmp_class_f32_e32 vcc, v25, v221
	v_add_f32_e32 v28, v35, v31
	v_mul_f32_e32 v28, 0xbfb8aa3b, v28
	v_cndmask_b32_e32 v25, v0, v25, vcc
	v_mul_f32_e32 v0, 0x41000000, v17
	v_mul_f32_e32 v0, v22, v0
	v_mul_f32_e32 v0, 0x3fb8aa3b, v0
	v_exp_f32_e32 v16, v0
	v_add_f32_e32 v0, v18, v26
	v_mul_f32_e32 v0, 0xbfb8aa3b, v0
	v_exp_f32_e32 v18, v0
	v_fma_f32 v0, -v16, v16, 1.0
	v_max_f32_e32 v0, 0, v0
	v_cmp_gt_f32_e32 vcc, s85, v0
	v_mul_f32_e32 v17, 0x4f800000, v0
	v_exp_f32_e32 v28, v28
	v_cndmask_b32_e32 v0, v0, v17, vcc
	v_sqrt_f32_e32 v17, v0
	v_add_f32_e32 v18, 1.0, v18
	v_rcp_f32_e32 v18, v18
	v_pk_mul_f32 v[20:21], v[20:21], v[24:25]
	v_add_u32_e32 v22, -1, v17
	v_fma_f32 v26, -v22, v17, v0
	v_cmp_ge_f32_e64 s[4:5], 0, v26
	v_add_u32_e32 v26, 1, v17
	s_nop 0
	v_cndmask_b32_e64 v22, v17, v22, s[4:5]
	v_fma_f32 v17, -v26, v17, v0
	v_cmp_lt_f32_e64 s[4:5], 0, v17
	s_nop 1
	v_cndmask_b32_e64 v17, v22, v26, s[4:5]
	v_add_f32_e32 v22, 1.0, v28
	v_rcp_f32_e32 v22, v22
	v_mul_f32_e32 v26, 0x37800000, v17
	v_cndmask_b32_e32 v26, v17, v26, vcc
	v_cmp_class_f32_e32 vcc, v0, v221
	v_mul_f32_e32 v17, 0x41000000, v22
	v_mul_f32_e32 v17, v23, v17
	v_mul_f32_e32 v17, 0x3fb8aa3b, v17
	v_exp_f32_e32 v17, v17
	s_nop 0
	v_fma_f32 v22, -v17, v17, 1.0
	v_max_f32_e32 v22, 0, v22
	v_cmp_gt_f32_e64 s[4:5], s85, v22
	v_mul_f32_e32 v23, 0x4f800000, v22
	s_nop 0
	v_cndmask_b32_e64 v23, v22, v23, s[4:5]
	v_sqrt_f32_e32 v27, v23
	v_cndmask_b32_e32 v22, v26, v0, vcc
	v_add_f32_e32 v0, 1.0, v19
	v_rcp_f32_e32 v19, v0
	v_add_u32_e32 v0, -1, v27
	v_fma_f32 v26, -v0, v27, v23
	v_cmp_ge_f32_e32 vcc, 0, v26
	v_add_u32_e32 v26, 1, v27
	s_nop 0
	v_cndmask_b32_e32 v0, v27, v0, vcc
	v_fma_f32 v27, -v26, v27, v23
	v_cmp_lt_f32_e32 vcc, 0, v27
	s_nop 1
	v_cndmask_b32_e32 v0, v0, v26, vcc
	v_mul_f32_e32 v26, 0x37800000, v0
	v_cndmask_b32_e64 v0, v0, v26, s[4:5]
	v_cmp_class_f32_e32 vcc, v23, v221
	s_nop 1
	v_cndmask_b32_e32 v23, v0, v23, vcc
	v_pk_mul_f32 v[22:23], v[18:19], v[22:23]
	v_pk_mul_f32 v[18:19], v[36:37], v[20:21]
	v_pk_mul_f32 v[20:21], v[38:39], v[22:23]
	ds_write_b128 v45, v[14:17] offset:128
	ds_write_b128 v44, v[18:21] offset:128
	global_store_dwordx4 v[40:41], v[14:17], off offset:128
	global_store_dwordx4 v[42:43], v[18:21], off offset:128
	ds_read_b128 v[14:17], v47 offset:16128
	ds_read_b128 v[24:27], v47 offset:16192
	s_waitcnt lgkmcnt(0)
	v_mfma_f32_16x16x32_bf16 v[14:17], v[14:17], v[10:13], 0
	ds_read_b128 v[28:31], v47 offset:6912
	ds_read_b128 v[32:35], v47 offset:6976
	ds_read_b128 v[20:23], v46 offset:704
	v_mfma_f32_16x16x32_bf16 v[24:27], v[24:27], v[6:9], v[14:17]
	s_waitcnt lgkmcnt(0)
	v_mfma_f32_16x16x32_bf16 v[16:19], v[28:31], v[10:13], 0
	s_nop 1
	ds_read_b128 v[12:15], v46 offset:192
	ds_read_b128 v[28:31], v44 offset:33984
	s_nop 1
	v_add_f32_e32 v0, v24, v20
	v_mul_f32_e32 v0, 0xbfb8aa3b, v0
	v_exp_f32_e32 v0, v0
	v_mfma_f32_16x16x32_bf16 v[8:11], v[32:35], v[6:9], v[16:19]
	v_add_f32_e32 v21, v25, v21
	v_mul_f32_e32 v21, 0xbfb8aa3b, v21
	v_add_f32_e32 v0, 1.0, v0
	v_rcp_f32_e32 v20, v0
	ds_read_b128 v[16:19], v46 offset:448
	v_exp_f32_e32 v21, v21
	v_add_f32_e32 v22, v26, v22
	v_mul_f32_e32 v6, 0x41000000, v20
	s_waitcnt lgkmcnt(0)
	v_mul_f32_e32 v6, v12, v6
	v_mul_f32_e32 v6, 0x3fb8aa3b, v6
	v_exp_f32_e32 v6, v6
	v_add_f32_e32 v7, v8, v16
	v_mul_f32_e32 v7, 0xbfb8aa3b, v7
	v_exp_f32_e32 v7, v7
	v_fma_f32 v8, -v6, v6, 1.0
	v_max_f32_e32 v8, 0, v8
	v_cmp_gt_f32_e32 vcc, s85, v8
	v_mul_f32_e32 v12, 0x4f800000, v8
	v_add_f32_e32 v7, 1.0, v7
	v_cndmask_b32_e32 v8, v8, v12, vcc
	v_sqrt_f32_e32 v16, v8
	v_rcp_f32_e32 v12, v7
	v_add_f32_e32 v9, v9, v17
	v_mul_f32_e32 v9, 0xbfb8aa3b, v9
	v_add_u32_e32 v7, -1, v16
	v_fma_f32 v24, -v7, v16, v8
	v_cmp_ge_f32_e64 s[4:5], 0, v24
	v_add_u32_e32 v24, 1, v16
	v_exp_f32_e32 v9, v9
	v_cndmask_b32_e64 v7, v16, v7, s[4:5]
	v_fma_f32 v16, -v24, v16, v8
	v_cmp_lt_f32_e64 s[4:5], 0, v16
	v_add_f32_e32 v16, 1.0, v21
	v_rcp_f32_e32 v16, v16
	v_cndmask_b32_e64 v7, v7, v24, s[4:5]
	v_mul_f32_e32 v21, 0x37800000, v7
	v_cndmask_b32_e32 v21, v7, v21, vcc
	v_mul_f32_e32 v7, 0x41000000, v16
	v_mul_f32_e32 v7, v13, v7
	v_mul_f32_e32 v7, 0x3fb8aa3b, v7
	v_exp_f32_e32 v7, v7
	v_cmp_class_f32_e32 vcc, v8, v221
	v_mul_f32_e32 v22, 0xbfb8aa3b, v22
	v_exp_f32_e32 v22, v22
	v_fma_f32 v13, -v7, v7, 1.0
	v_max_f32_e32 v13, 0, v13
	v_cmp_gt_f32_e64 s[4:5], s85, v13
	v_mul_f32_e32 v16, 0x4f800000, v13
	v_add_f32_e32 v11, v11, v19
	v_cndmask_b32_e64 v17, v13, v16, s[4:5]
	v_sqrt_f32_e32 v24, v17
	v_cndmask_b32_e32 v16, v21, v8, vcc
	v_add_f32_e32 v8, 1.0, v9
	v_rcp_f32_e32 v13, v8
	v_add_u32_e32 v8, -1, v24
	v_fma_f32 v9, -v8, v24, v17
	v_cmp_ge_f32_e32 vcc, 0, v9
	v_add_u32_e32 v9, 1, v24
	v_fma_f32 v21, -v9, v24, v17
	v_cndmask_b32_e32 v8, v24, v8, vcc
	v_cmp_lt_f32_e32 vcc, 0, v21
	v_add_f32_e32 v21, 1.0, v22
	v_rcp_f32_e32 v21, v21
	v_cndmask_b32_e32 v8, v8, v9, vcc
	v_mul_f32_e32 v9, 0x37800000, v8
	v_cndmask_b32_e64 v8, v8, v9, s[4:5]
	v_cmp_class_f32_e32 vcc, v17, v221
	v_add_f32_e32 v9, v10, v18
	v_mul_f32_e32 v9, 0xbfb8aa3b, v9
	v_cndmask_b32_e32 v17, v8, v17, vcc
	v_mul_f32_e32 v8, 0x41000000, v21
	v_mul_f32_e32 v8, v14, v8
	v_mul_f32_e32 v8, 0x3fb8aa3b, v8
	v_exp_f32_e32 v8, v8
	v_exp_f32_e32 v14, v9
	v_add_f32_e32 v22, v27, v23
	v_mul_f32_e32 v22, 0xbfb8aa3b, v22
	v_fma_f32 v9, -v8, v8, 1.0
	v_max_f32_e32 v9, 0, v9
	v_cmp_gt_f32_e32 vcc, s85, v9
	v_mul_f32_e32 v10, 0x4f800000, v9
	v_exp_f32_e32 v22, v22
	v_cndmask_b32_e32 v10, v9, v10, vcc
	v_sqrt_f32_e32 v9, v10
	v_mul_f32_e32 v11, 0xbfb8aa3b, v11
	v_exp_f32_e32 v11, v11
	v_add_f32_e32 v14, 1.0, v14
	v_add_u32_e32 v18, -1, v9
	v_fma_f32 v21, -v18, v9, v10
	v_cmp_ge_f32_e64 s[4:5], 0, v21
	v_add_u32_e32 v21, 1, v9
	v_add_f32_e32 v11, 1.0, v11
	v_cndmask_b32_e64 v18, v9, v18, s[4:5]
	v_fma_f32 v9, -v21, v9, v10
	v_cmp_lt_f32_e64 s[4:5], 0, v9
	v_rcp_f32_e32 v14, v14
	v_and_b32_e32 v0, 63, v2
	v_cndmask_b32_e64 v9, v18, v21, s[4:5]
	v_add_f32_e32 v18, 1.0, v22
	v_rcp_f32_e32 v18, v18
	v_mul_f32_e32 v21, 0x37800000, v9
	v_cndmask_b32_e32 v21, v9, v21, vcc
	v_cmp_class_f32_e32 vcc, v10, v221
	v_mul_f32_e32 v9, 0x41000000, v18
	v_mul_f32_e32 v9, v15, v9
	v_mul_f32_e32 v9, 0x3fb8aa3b, v9
	v_exp_f32_e32 v9, v9
	v_cndmask_b32_e32 v10, v21, v10, vcc
	v_pk_mul_f32 v[12:13], v[12:13], v[16:17]
	v_and_b32_e32 v20, -16, v3
	v_fma_f32 v15, -v9, v9, 1.0
	v_max_f32_e32 v15, 0, v15
	v_cmp_gt_f32_e64 s[4:5], s85, v15
	v_mul_f32_e32 v18, 0x4f800000, v15
	v_lshlrev_b32_e32 v0, 2, v0
	v_cndmask_b32_e64 v18, v15, v18, s[4:5]
	v_sqrt_f32_e32 v19, v18
	v_rcp_f32_e32 v15, v11
	v_add_u32_e32 v11, -1, v19
	v_fma_f32 v21, -v11, v19, v18
	v_cmp_ge_f32_e32 vcc, 0, v21
	v_add_u32_e32 v21, 1, v19
	s_nop 0
	v_cndmask_b32_e32 v11, v19, v11, vcc
	v_fma_f32 v19, -v21, v19, v18
	v_cmp_lt_f32_e32 vcc, 0, v19
	s_nop 1
	v_cndmask_b32_e32 v11, v11, v21, vcc
	v_mul_f32_e32 v19, 0x37800000, v11
	v_cndmask_b32_e64 v11, v11, v19, s[4:5]
	v_cmp_class_f32_e32 vcc, v18, v221
	s_movk_i32 s4, 0xf000
	s_nop 0
	v_cndmask_b32_e32 v11, v11, v18, vcc
	v_pk_mul_f32 v[14:15], v[14:15], v[10:11]
	v_pk_mul_f32 v[10:11], v[28:29], v[12:13]
	v_pk_mul_f32 v[12:13], v[30:31], v[14:15]
	ds_write_b128 v45, v[6:9] offset:192
	ds_write_b128 v44, v[10:13] offset:192
	global_store_dwordx4 v[40:41], v[6:9], off offset:192
	global_store_dwordx4 v[42:43], v[10:13], off offset:192
	s_waitcnt lgkmcnt(0)
	v_or_b32_e32 v6, 15, v3
	v_lshlrev_b32_e32 v3, 8, v3
	v_and_or_b32 v3, v3, s4, v0
	v_sub_u32_e32 v6, v6, v20
	v_add_u32_e32 v3, 0, v3
	v_add_u32_e32 v10, 1, v6
	v_mov_b32_e32 v7, 1.0
	v_mov_b32_e32 v8, 0
	s_mov_b64 s[4:5], 0
	s_barrier
